# mlstm_local: this thread's K/V pieces touched before the staging loop (loop loads become cache hits)
# baseline (speedup 1.0000x reference)
; __device__ __forceinline__ void mlstm_local(const Params& P, unsigned char* shm, int bh, int j) {
;     ...
;     const int L = j == 0 ? 16 : 128; const int rowb = j == 0 ? ROW_META : b * 2048 + (j - 1) * 128;
;     const int niter = j == 0 ? 2 : 8;
; #pragma unroll 2
;     for (int i = 0; i < niter; ++i) { const int item = tid + 512 * i; const int s = ((item >> 9) << 4) | (item & 15), c8 = (item >> 4) & 31;
;         u32x4 kw = (u32x4){0u, 0u, 0u, 0u}, vw = (u32x4){0u, 0u, 0u, 0u}; float w = 0.f;
;         if (s < L) { const bf16_t* rp = PROJ + (size_t)(rowb + s) * NPROJ + h * 256 + c8 * 8; kw = *(const u32x4*)(rp + C_K); vw = *(const u32x4*)(rp + C_V); w = __expf(sm[s] - Ml) * 0.0625f; }
.LBB0_333:
	s_or_b64 exec, exec, s[0:1]
	s_waitcnt lgkmcnt(0)
	v_max_f32_e32 v0, v1, v1
	v_max_f32_e32 v1, v2, v2
	s_lshl_b32 s1, s73, 11
	v_max_f32_e32 v10, v1, v0
	s_lshl_b32 s0, s72, 7
	v_or_b32_e32 v0, s1, v93
	s_lshl_b32 s84, s74, 9
	v_or_b32_e32 v11, s0, v0
	v_or_b32_e32 v0, s1, v94
	v_lshl_add_u64 v[8:9], v[74:75], 0, s[84:85]
	v_or_b32_e32 v12, s0, v0
	s_mov_b32 s11, 0
	v_mov_b32_e32 v13, v96
	v_mov_b32_e32 v14, v95
	v_mov_b32_e32 v15, v92
	s_waitcnt vmcnt(12)
	v_mov_b32_e32 v16, v91
	v_mov_b32_e32 v17, v86
	v_add_u32_e32 v120, 0, v12
	v_mad_i64_i32 v[122:123], s[0:1], v120, s89, v[8:9]
	v_add_co_u32_e32 v122, vcc, 0x1000, v122
	s_nop 1
	v_addc_co_u32_e32 v123, vcc, 0, v123, vcc
	global_load_dwordx4 v[150:153], v[122:123], off
	global_load_dwordx4 v[154:157], v[122:123], off offset:2048
	v_add_u32_e32 v120, 0, v11
	v_mad_i64_i32 v[122:123], s[0:1], v120, s89, v[8:9]
	v_add_co_u32_e32 v122, vcc, 0x1000, v122
	s_nop 1
	v_addc_co_u32_e32 v123, vcc, 0, v123, vcc
	global_load_dwordx4 v[158:161], v[122:123], off
	global_load_dwordx4 v[162:165], v[122:123], off offset:2048
	v_add_u32_e32 v120, 32, v12
	v_mad_i64_i32 v[122:123], s[0:1], v120, s89, v[8:9]
	v_add_co_u32_e32 v122, vcc, 0x1000, v122
	s_nop 1
	v_addc_co_u32_e32 v123, vcc, 0, v123, vcc
	global_load_dwordx4 v[166:169], v[122:123], off
	global_load_dwordx4 v[170:173], v[122:123], off offset:2048
	v_add_u32_e32 v120, 32, v11
	v_mad_i64_i32 v[122:123], s[0:1], v120, s89, v[8:9]
	v_add_co_u32_e32 v122, vcc, 0x1000, v122
	s_nop 1
	v_addc_co_u32_e32 v123, vcc, 0, v123, vcc
	global_load_dwordx4 v[174:177], v[122:123], off
	global_load_dwordx4 v[178:181], v[122:123], off offset:2048
	v_add_u32_e32 v120, 64, v12
	v_mad_i64_i32 v[122:123], s[0:1], v120, s89, v[8:9]
	v_add_co_u32_e32 v122, vcc, 0x1000, v122
	s_nop 1
	v_addc_co_u32_e32 v123, vcc, 0, v123, vcc
	global_load_dwordx4 v[182:185], v[122:123], off
	global_load_dwordx4 v[186:189], v[122:123], off offset:2048
	v_add_u32_e32 v120, 64, v11
	v_mad_i64_i32 v[122:123], s[0:1], v120, s89, v[8:9]
	v_add_co_u32_e32 v122, vcc, 0x1000, v122
	s_nop 1
	v_addc_co_u32_e32 v123, vcc, 0, v123, vcc
	global_load_dwordx4 v[190:193], v[122:123], off
	global_load_dwordx4 v[194:197], v[122:123], off offset:2048
	v_add_u32_e32 v120, 96, v12
	v_mad_i64_i32 v[122:123], s[0:1], v120, s89, v[8:9]
	v_add_co_u32_e32 v122, vcc, 0x1000, v122
	s_nop 1
	v_addc_co_u32_e32 v123, vcc, 0, v123, vcc
	global_load_dwordx4 v[198:201], v[122:123], off
	global_load_dwordx4 v[202:205], v[122:123], off offset:2048
	v_add_u32_e32 v120, 96, v11
	v_mad_i64_i32 v[122:123], s[0:1], v120, s89, v[8:9]
	v_add_co_u32_e32 v122, vcc, 0x1000, v122
	s_nop 1
	v_addc_co_u32_e32 v123, vcc, 0, v123, vcc
	global_load_dwordx4 v[206:209], v[122:123], off
	global_load_dwordx4 v[210:213], v[122:123], off offset:2048
	s_branch .LBB0_335
